# FFN-up SwiGLU epilogue re-emitted in independent batches of 8 with packed add/mul (on foldfix+attention)
# speedup vs baseline: 1.0106x; 1.0106x over previous
.LBB0_555:
	s_add_u32 s2, s6, 0xfffc0080
	s_addc_u32 s3, s7, -1
	s_add_i32 s77, 0, 0x10000
	v_add_u32_e32 v150, s77, v139
	ds_read_b128 v[134:137], v150
	ds_read_b128 v[142:145], v150 offset:1024
	ds_read_b128 v[146:149], v150 offset:2048
	ds_read_b128 v[150:153], v150 offset:3072
	s_cmp_eq_u32 s73, 12
	s_cselect_b32 s3, s10, s3
	s_cselect_b32 s2, s24, s2
	s_cselect_b32 s55, s25, s69
	s_cselect_b32 s54, s41, s43
	v_lshl_add_u64 v[154:155], s[6:7], 0, v[132:133]
	s_add_i32 m0, s47, 0xc000
	ds_read_b128 v[162:165], v141
	ds_read_b128 v[166:169], v141 offset:1024
	ds_read_b128 v[170:173], v141 offset:2048
	ds_read_b128 v[174:177], v141 offset:3072
	ds_read_b128 v[178:181], v141 offset:4096
	ds_read_b128 v[182:185], v141 offset:5120
	ds_read_b128 v[186:189], v141 offset:6144
	ds_read_b128 v[214:217], v141 offset:7168
	global_load_lds_dwordx4 v[154:155], off
	v_lshl_add_u64 v[154:155], s[6:7], 0, v[130:131]
	s_add_i32 m0, s47, 0xe000
	s_nop 0
	global_load_lds_dwordx4 v[154:155], off
	s_waitcnt lgkmcnt(8)
	s_barrier
	s_waitcnt lgkmcnt(0)
	s_setprio 1
	s_waitcnt lgkmcnt(0)
	v_mfma_f32_16x16x32_bf16 v[124:127], v[134:137], v[162:165], v[124:127]
	v_mfma_f32_16x16x32_bf16 v[116:119], v[146:149], v[162:165], v[116:119]
	v_mfma_f32_16x16x32_bf16 v[108:111], v[134:137], v[170:173], v[108:111]
	v_mfma_f32_16x16x32_bf16 v[100:103], v[146:149], v[170:173], v[100:103]
	v_mfma_f32_16x16x32_bf16 v[92:95], v[134:137], v[178:181], v[92:95]
	v_mfma_f32_16x16x32_bf16 v[84:87], v[146:149], v[178:181], v[84:87]
	v_mfma_f32_16x16x32_bf16 v[76:79], v[134:137], v[186:189], v[76:79]
	v_mfma_f32_16x16x32_bf16 v[68:71], v[146:149], v[186:189], v[68:71]
	v_mfma_f32_16x16x32_bf16 v[124:127], v[142:145], v[166:169], v[124:127]
	v_mfma_f32_16x16x32_bf16 v[116:119], v[150:153], v[166:169], v[116:119]
	v_mfma_f32_16x16x32_bf16 v[108:111], v[142:145], v[174:177], v[108:111]
	v_mfma_f32_16x16x32_bf16 v[100:103], v[150:153], v[174:177], v[100:103]
	v_mfma_f32_16x16x32_bf16 v[92:95], v[142:145], v[182:185], v[92:95]
	v_mfma_f32_16x16x32_bf16 v[84:87], v[150:153], v[182:185], v[84:87]
	v_mfma_f32_16x16x32_bf16 v[76:79], v[142:145], v[214:217], v[76:79]
	v_mfma_f32_16x16x32_bf16 v[68:71], v[150:153], v[214:217], v[68:71]
	s_setprio 0
	s_barrier
	s_add_i32 s80, 0, 0x14000
	v_add_u32_e32 v154, s80, v139
	s_add_i32 s77, s77, s53
	ds_read_b128 v[218:221], v154
	ds_read_b128 v[222:225], v154 offset:1024
	ds_read_b128 v[226:229], v154 offset:2048
	ds_read_b128 v[230:233], v154 offset:3072
	v_lshl_add_u64 v[154:155], s[54:55], 0, v[156:157]
	s_mov_b32 m0, s77
	v_lshl_add_u64 v[206:207], s[54:55], 0, v[128:129]
	global_load_lds_dwordx4 v[154:155], off
	s_add_i32 m0, s77, 0x2000
	s_nop 0
	global_load_lds_dwordx4 v[206:207], off
	s_barrier
	s_waitcnt lgkmcnt(0)
	s_setprio 1
	s_waitcnt lgkmcnt(0)
	v_mfma_f32_16x16x32_bf16 v[120:123], v[218:221], v[162:165], v[120:123]
	v_mfma_f32_16x16x32_bf16 v[112:115], v[226:229], v[162:165], v[112:115]
	v_mfma_f32_16x16x32_bf16 v[104:107], v[218:221], v[170:173], v[104:107]
	v_mfma_f32_16x16x32_bf16 v[96:99], v[226:229], v[170:173], v[96:99]
	v_mfma_f32_16x16x32_bf16 v[88:91], v[218:221], v[178:181], v[88:91]
	v_mfma_f32_16x16x32_bf16 v[80:83], v[226:229], v[178:181], v[80:83]
	v_mfma_f32_16x16x32_bf16 v[72:75], v[218:221], v[186:189], v[72:75]
	v_mfma_f32_16x16x32_bf16 v[64:67], v[226:229], v[186:189], v[64:67]
	v_mfma_f32_16x16x32_bf16 v[120:123], v[222:225], v[166:169], v[120:123]
	v_mfma_f32_16x16x32_bf16 v[112:115], v[230:233], v[166:169], v[112:115]
	v_mfma_f32_16x16x32_bf16 v[104:107], v[222:225], v[174:177], v[104:107]
	v_mfma_f32_16x16x32_bf16 v[96:99], v[230:233], v[174:177], v[96:99]
	v_mfma_f32_16x16x32_bf16 v[88:91], v[222:225], v[182:185], v[88:91]
	v_mfma_f32_16x16x32_bf16 v[80:83], v[230:233], v[182:185], v[80:83]
	v_mfma_f32_16x16x32_bf16 v[72:75], v[222:225], v[214:217], v[72:75]
	v_mfma_f32_16x16x32_bf16 v[64:67], v[230:233], v[214:217], v[64:67]
	s_setprio 0
	s_mov_b32 m0, s47
	v_lshl_add_u64 v[208:209], s[2:3], 0, v[156:157]
	s_barrier
	ds_read_b128 v[162:165], v141 offset:16384
	ds_read_b128 v[166:169], v141 offset:17408
	ds_read_b128 v[170:173], v141 offset:18432
	ds_read_b128 v[174:177], v141 offset:19456
	ds_read_b128 v[178:181], v141 offset:20480
	ds_read_b128 v[182:185], v141 offset:21504
	ds_read_b128 v[186:189], v141 offset:22528
	ds_read_b128 v[214:217], v141 offset:23552
	global_load_lds_dwordx4 v[208:209], off
	v_lshl_add_u64 v[234:235], s[2:3], 0, v[128:129]
	s_mov_b32 m0, s49
	s_nop 0
	global_load_lds_dwordx4 v[234:235], off
	s_barrier
	s_waitcnt lgkmcnt(0)
	s_setprio 1
	s_waitcnt lgkmcnt(0)
	v_mfma_f32_16x16x32_bf16 v[60:63], v[134:137], v[162:165], v[60:63]
	v_mfma_f32_16x16x32_bf16 v[52:55], v[146:149], v[162:165], v[52:55]
	v_mfma_f32_16x16x32_bf16 v[44:47], v[134:137], v[170:173], v[44:47]
	v_mfma_f32_16x16x32_bf16 v[36:39], v[146:149], v[170:173], v[36:39]
	v_mfma_f32_16x16x32_bf16 v[28:31], v[134:137], v[178:181], v[28:31]
	v_mfma_f32_16x16x32_bf16 v[20:23], v[146:149], v[178:181], v[20:23]
	v_mfma_f32_16x16x32_bf16 v[12:15], v[134:137], v[186:189], v[12:15]
	v_mfma_f32_16x16x32_bf16 v[4:7], v[146:149], v[186:189], v[4:7]
	v_mfma_f32_16x16x32_bf16 v[60:63], v[142:145], v[166:169], v[60:63]
	v_mfma_f32_16x16x32_bf16 v[52:55], v[150:153], v[166:169], v[52:55]
	v_mfma_f32_16x16x32_bf16 v[44:47], v[142:145], v[174:177], v[44:47]
	v_mfma_f32_16x16x32_bf16 v[36:39], v[150:153], v[174:177], v[36:39]
	v_mfma_f32_16x16x32_bf16 v[28:31], v[142:145], v[182:185], v[28:31]
	v_mfma_f32_16x16x32_bf16 v[20:23], v[150:153], v[182:185], v[20:23]
	v_mfma_f32_16x16x32_bf16 v[12:15], v[142:145], v[214:217], v[12:15]
	v_mfma_f32_16x16x32_bf16 v[4:7], v[150:153], v[214:217], v[4:7]
	s_setprio 0
	s_barrier
	s_add_u32 s78, s54, 0x40000
	s_addc_u32 s79, s55, 0
	s_add_i32 s77, s80, s53
	v_lshl_add_u64 v[134:135], s[78:79], 0, v[156:157]
	s_mov_b32 m0, s77
	s_nop 0
	global_load_lds_dwordx4 v[134:135], off
	v_lshl_add_u64 v[134:135], s[78:79], 0, v[128:129]
	s_add_i32 m0, s77, 0x2000
	s_nop 0
	global_load_lds_dwordx4 v[134:135], off
	s_waitcnt vmcnt(6)
	s_barrier
	s_setprio 1
	v_mfma_f32_16x16x32_bf16 v[56:59], v[218:221], v[162:165], v[56:59]
	v_mfma_f32_16x16x32_bf16 v[48:51], v[226:229], v[162:165], v[48:51]
	v_mfma_f32_16x16x32_bf16 v[40:43], v[218:221], v[170:173], v[40:43]
	v_mfma_f32_16x16x32_bf16 v[32:35], v[226:229], v[170:173], v[32:35]
	v_mfma_f32_16x16x32_bf16 v[24:27], v[218:221], v[178:181], v[24:27]
	v_mfma_f32_16x16x32_bf16 v[16:19], v[226:229], v[178:181], v[16:19]
	v_mfma_f32_16x16x32_bf16 v[8:11], v[218:221], v[186:189], v[8:11]
	v_mfma_f32_16x16x32_bf16 v[0:3], v[226:229], v[186:189], v[0:3]
	v_mfma_f32_16x16x32_bf16 v[56:59], v[222:225], v[166:169], v[56:59]
	v_mfma_f32_16x16x32_bf16 v[48:51], v[230:233], v[166:169], v[48:51]
	v_mfma_f32_16x16x32_bf16 v[40:43], v[222:225], v[174:177], v[40:43]
	v_mfma_f32_16x16x32_bf16 v[32:35], v[230:233], v[174:177], v[32:35]
	v_mfma_f32_16x16x32_bf16 v[24:27], v[222:225], v[182:185], v[24:27]
	v_mfma_f32_16x16x32_bf16 v[16:19], v[230:233], v[182:185], v[16:19]
	v_mfma_f32_16x16x32_bf16 v[8:11], v[222:225], v[214:217], v[8:11]
	v_mfma_f32_16x16x32_bf16 v[0:3], v[230:233], v[214:217], v[0:3]
	s_setprio 0
	s_add_i32 s77, 0, 0x18000
	v_add_u32_e32 v150, s77, v139
	s_barrier
	ds_read_b128 v[134:137], v150
	ds_read_b128 v[142:145], v150 offset:1024
	ds_read_b128 v[146:149], v150 offset:2048
	ds_read_b128 v[150:153], v150 offset:3072
	s_add_u32 s2, s2, 0x40000
	s_addc_u32 s3, s3, 0
	s_mov_b32 m0, s62
	v_lshl_add_u64 v[218:219], s[2:3], 0, v[156:157]
	ds_read_b128 v[162:165], v141 offset:32768
	ds_read_b128 v[166:169], v141 offset:33792
	ds_read_b128 v[170:173], v141 offset:34816
	ds_read_b128 v[174:177], v141 offset:35840
	ds_read_b128 v[178:181], v141 offset:36864
	ds_read_b128 v[182:185], v141 offset:37888
	ds_read_b128 v[186:189], v141 offset:38912
	ds_read_b128 v[214:217], v141 offset:39936
	global_load_lds_dwordx4 v[218:219], off
	v_lshl_add_u64 v[218:219], s[2:3], 0, v[128:129]
	s_mov_b32 m0, s63
	s_nop 0
	global_load_lds_dwordx4 v[218:219], off
	s_waitcnt lgkmcnt(8)
	s_barrier
	s_waitcnt lgkmcnt(0)
	s_setprio 1
	s_waitcnt lgkmcnt(0)
	v_mfma_f32_16x16x32_bf16 v[124:127], v[134:137], v[162:165], v[124:127]
	v_mfma_f32_16x16x32_bf16 v[116:119], v[146:149], v[162:165], v[116:119]
	v_mfma_f32_16x16x32_bf16 v[108:111], v[134:137], v[170:173], v[108:111]
	v_mfma_f32_16x16x32_bf16 v[100:103], v[146:149], v[170:173], v[100:103]
	v_mfma_f32_16x16x32_bf16 v[92:95], v[134:137], v[178:181], v[92:95]
	v_mfma_f32_16x16x32_bf16 v[84:87], v[146:149], v[178:181], v[84:87]
	v_mfma_f32_16x16x32_bf16 v[76:79], v[134:137], v[186:189], v[76:79]
	v_mfma_f32_16x16x32_bf16 v[68:71], v[146:149], v[186:189], v[68:71]
	v_mfma_f32_16x16x32_bf16 v[124:127], v[142:145], v[166:169], v[124:127]
	v_mfma_f32_16x16x32_bf16 v[116:119], v[150:153], v[166:169], v[116:119]
	v_mfma_f32_16x16x32_bf16 v[108:111], v[142:145], v[174:177], v[108:111]
	v_mfma_f32_16x16x32_bf16 v[100:103], v[150:153], v[174:177], v[100:103]
	v_mfma_f32_16x16x32_bf16 v[92:95], v[142:145], v[182:185], v[92:95]
	v_mfma_f32_16x16x32_bf16 v[84:87], v[150:153], v[182:185], v[84:87]
	v_mfma_f32_16x16x32_bf16 v[76:79], v[142:145], v[214:217], v[76:79]
	v_mfma_f32_16x16x32_bf16 v[68:71], v[150:153], v[214:217], v[68:71]
	s_setprio 0
	s_barrier
	s_add_i32 s78, 0, 0x1c000
	s_add_i32 s2, s77, s53
	v_add_u32_e32 v161, s78, v139
	v_lshl_add_u64 v[154:155], v[154:155], 0, s[50:51]
	s_mov_b32 m0, s2
	ds_read_b128 v[218:221], v161
	ds_read_b128 v[222:225], v161 offset:1024
	ds_read_b128 v[226:229], v161 offset:2048
	ds_read_b128 v[230:233], v161 offset:3072
	global_load_lds_dwordx4 v[154:155], off
	v_lshl_add_u64 v[154:155], v[206:207], 0, s[50:51]
	s_add_i32 m0, s2, 0x2000
	s_nop 0
	global_load_lds_dwordx4 v[154:155], off
	s_barrier
	s_waitcnt lgkmcnt(0)
	s_setprio 1
	s_waitcnt lgkmcnt(0)
	v_mfma_f32_16x16x32_bf16 v[120:123], v[218:221], v[162:165], v[120:123]
	v_mfma_f32_16x16x32_bf16 v[112:115], v[226:229], v[162:165], v[112:115]
	v_mfma_f32_16x16x32_bf16 v[104:107], v[218:221], v[170:173], v[104:107]
	v_mfma_f32_16x16x32_bf16 v[96:99], v[226:229], v[170:173], v[96:99]
	v_mfma_f32_16x16x32_bf16 v[88:91], v[218:221], v[178:181], v[88:91]
	v_mfma_f32_16x16x32_bf16 v[80:83], v[226:229], v[178:181], v[80:83]
	v_mfma_f32_16x16x32_bf16 v[72:75], v[218:221], v[186:189], v[72:75]
	v_mfma_f32_16x16x32_bf16 v[64:67], v[226:229], v[186:189], v[64:67]
	v_mfma_f32_16x16x32_bf16 v[120:123], v[222:225], v[166:169], v[120:123]
	v_mfma_f32_16x16x32_bf16 v[112:115], v[230:233], v[166:169], v[112:115]
	v_mfma_f32_16x16x32_bf16 v[104:107], v[222:225], v[174:177], v[104:107]
	v_mfma_f32_16x16x32_bf16 v[96:99], v[230:233], v[174:177], v[96:99]
	v_mfma_f32_16x16x32_bf16 v[88:91], v[222:225], v[182:185], v[88:91]
	v_mfma_f32_16x16x32_bf16 v[80:83], v[230:233], v[182:185], v[80:83]
	v_mfma_f32_16x16x32_bf16 v[72:75], v[222:225], v[214:217], v[72:75]
	v_mfma_f32_16x16x32_bf16 v[64:67], v[230:233], v[214:217], v[64:67]
	s_setprio 0
	s_mov_b32 m0, s66
	v_lshl_add_u64 v[154:155], v[208:209], 0, s[50:51]
	s_barrier
	ds_read_b128 v[162:165], v141 offset:49152
	ds_read_b128 v[166:169], v141 offset:50176
	ds_read_b128 v[170:173], v141 offset:51200
	ds_read_b128 v[174:177], v141 offset:52224
	ds_read_b128 v[178:181], v141 offset:53248
	ds_read_b128 v[182:185], v141 offset:54272
	ds_read_b128 v[186:189], v141 offset:55296
	ds_read_b128 v[214:217], v141 offset:56320
	global_load_lds_dwordx4 v[154:155], off
	v_lshl_add_u64 v[154:155], v[234:235], 0, s[50:51]
	s_mov_b32 m0, s67
	s_nop 0
	global_load_lds_dwordx4 v[154:155], off
	s_barrier
	s_waitcnt lgkmcnt(0)
	s_setprio 1
	s_waitcnt lgkmcnt(0)
	v_mfma_f32_16x16x32_bf16 v[60:63], v[134:137], v[162:165], v[60:63]
	v_mfma_f32_16x16x32_bf16 v[52:55], v[146:149], v[162:165], v[52:55]
	v_mfma_f32_16x16x32_bf16 v[44:47], v[134:137], v[170:173], v[44:47]
	v_mfma_f32_16x16x32_bf16 v[36:39], v[146:149], v[170:173], v[36:39]
	v_mfma_f32_16x16x32_bf16 v[28:31], v[134:137], v[178:181], v[28:31]
	v_mfma_f32_16x16x32_bf16 v[20:23], v[146:149], v[178:181], v[20:23]
	v_mfma_f32_16x16x32_bf16 v[12:15], v[134:137], v[186:189], v[12:15]
	v_mfma_f32_16x16x32_bf16 v[4:7], v[146:149], v[186:189], v[4:7]
	v_mfma_f32_16x16x32_bf16 v[60:63], v[142:145], v[166:169], v[60:63]
	v_mfma_f32_16x16x32_bf16 v[52:55], v[150:153], v[166:169], v[52:55]
	v_mfma_f32_16x16x32_bf16 v[44:47], v[142:145], v[174:177], v[44:47]
	v_mfma_f32_16x16x32_bf16 v[36:39], v[150:153], v[174:177], v[36:39]
	v_mfma_f32_16x16x32_bf16 v[28:31], v[142:145], v[182:185], v[28:31]
	v_mfma_f32_16x16x32_bf16 v[20:23], v[150:153], v[182:185], v[20:23]
	v_mfma_f32_16x16x32_bf16 v[12:15], v[142:145], v[214:217], v[12:15]
	v_mfma_f32_16x16x32_bf16 v[4:7], v[150:153], v[214:217], v[4:7]
	s_setprio 0
	s_barrier
	s_add_u32 s2, s54, 0x40080
	s_addc_u32 s3, s55, 0
	s_add_i32 s54, s78, s53
	v_lshl_add_u64 v[134:135], s[2:3], 0, v[156:157]
	s_mov_b32 m0, s54
	s_nop 0
	global_load_lds_dwordx4 v[134:135], off
	v_lshl_add_u64 v[134:135], s[2:3], 0, v[128:129]
	s_add_i32 m0, s54, 0x2000
	s_nop 0
	global_load_lds_dwordx4 v[134:135], off
	s_waitcnt vmcnt(6)
	s_barrier
	s_setprio 1
	v_mfma_f32_16x16x32_bf16 v[56:59], v[218:221], v[162:165], v[56:59]
	v_mfma_f32_16x16x32_bf16 v[48:51], v[226:229], v[162:165], v[48:51]
	v_mfma_f32_16x16x32_bf16 v[40:43], v[218:221], v[170:173], v[40:43]
	v_mfma_f32_16x16x32_bf16 v[32:35], v[226:229], v[170:173], v[32:35]
	v_mfma_f32_16x16x32_bf16 v[24:27], v[218:221], v[178:181], v[24:27]
	v_mfma_f32_16x16x32_bf16 v[16:19], v[226:229], v[178:181], v[16:19]
	v_mfma_f32_16x16x32_bf16 v[8:11], v[218:221], v[186:189], v[8:11]
	v_mfma_f32_16x16x32_bf16 v[0:3], v[226:229], v[186:189], v[0:3]
	v_mfma_f32_16x16x32_bf16 v[56:59], v[222:225], v[166:169], v[56:59]
	v_mfma_f32_16x16x32_bf16 v[48:51], v[230:233], v[166:169], v[48:51]
	v_mfma_f32_16x16x32_bf16 v[40:43], v[222:225], v[174:177], v[40:43]
	v_mfma_f32_16x16x32_bf16 v[32:35], v[230:233], v[174:177], v[32:35]
	v_mfma_f32_16x16x32_bf16 v[24:27], v[222:225], v[182:185], v[24:27]
	v_mfma_f32_16x16x32_bf16 v[16:19], v[230:233], v[182:185], v[16:19]
	v_mfma_f32_16x16x32_bf16 v[8:11], v[222:225], v[214:217], v[8:11]
	v_mfma_f32_16x16x32_bf16 v[0:3], v[230:233], v[214:217], v[0:3]
	s_setprio 0
	s_add_i32 s73, s73, 2
	s_add_u32 s43, s43, 0x100
	s_addc_u32 s69, s69, 0
	s_add_u32 s6, s6, 0x100
	s_addc_u32 s7, s7, 0
	s_cmp_gt_u32 s73, 13
	s_barrier
	s_cbranch_scc0 .LBB0_555
	v_lshl_or_b32 v136, s46, 7, v140
	v_lshl_add_u32 v142, s48, 8, v138
	v_ashrrev_i32_e32 v137, 31, v136
	v_mov_b64_e32 v[134:135], s[30:31]
	v_lshlrev_b64 v[136:137], 1, v[136:137]
	s_and_b64 vcc, exec, s[38:39]
	s_mov_b32 s48, s42
	s_mov_b32 s46, s40
	v_mad_i64_i32 v[144:145], s[2:3], v142, s33, v[134:135]
	v_or_b32_e32 v186, 16, v142
	v_mul_f32_e32 v162, 0xbfb8aa3b, v124
	v_mad_i64_i32 v[186:187], s[2:3], v186, s33, v[134:135]
	v_mul_f32_e32 v163, 0xbfb8aa3b, v125
	v_mul_f32_e32 v170, 0xbfb8aa3b, v108
	v_mul_f32_e32 v164, 0xbfb8aa3b, v126
	v_mul_f32_e32 v171, 0xbfb8aa3b, v109
	v_mul_f32_e32 v165, 0xbfb8aa3b, v127
	v_mul_f32_e32 v172, 0xbfb8aa3b, v110
	v_mul_f32_e32 v166, 0xbfb8aa3b, v116
	v_mul_f32_e32 v173, 0xbfb8aa3b, v111
	v_mul_f32_e32 v167, 0xbfb8aa3b, v117
	v_mul_f32_e32 v174, 0xbfb8aa3b, v100
	v_mul_f32_e32 v168, 0xbfb8aa3b, v118
	v_mul_f32_e32 v175, 0xbfb8aa3b, v101
	v_mul_f32_e32 v169, 0xbfb8aa3b, v119
	v_mul_f32_e32 v176, 0xbfb8aa3b, v102
	v_lshl_add_u64 v[144:145], v[144:145], 0, v[136:137]
	v_mul_f32_e32 v177, 0xbfb8aa3b, v103
	v_exp_f32_e32 v162, v162
	v_lshl_add_u64 v[186:187], v[186:187], 0, v[136:137]
	v_exp_f32_e32 v163, v163
	v_exp_f32_e32 v170, v170
	v_exp_f32_e32 v164, v164
	v_exp_f32_e32 v171, v171
	v_exp_f32_e32 v165, v165
	v_exp_f32_e32 v172, v172
	v_exp_f32_e32 v166, v166
	v_exp_f32_e32 v173, v173
	v_exp_f32_e32 v167, v167
	v_exp_f32_e32 v174, v174
	v_exp_f32_e32 v168, v168
	v_exp_f32_e32 v175, v175
	v_exp_f32_e32 v169, v169
	v_exp_f32_e32 v176, v176
	v_pk_add_f32 v[162:163], v[162:163], 1.0 op_sel_hi:[1,0]
	v_exp_f32_e32 v177, v177
	v_pk_add_f32 v[164:165], v[164:165], 1.0 op_sel_hi:[1,0]
	v_pk_add_f32 v[170:171], v[170:171], 1.0 op_sel_hi:[1,0]
	v_pk_add_f32 v[166:167], v[166:167], 1.0 op_sel_hi:[1,0]
	v_pk_add_f32 v[172:173], v[172:173], 1.0 op_sel_hi:[1,0]
	v_pk_add_f32 v[168:169], v[168:169], 1.0 op_sel_hi:[1,0]
	v_pk_add_f32 v[174:175], v[174:175], 1.0 op_sel_hi:[1,0]
	v_rcp_f32_e32 v162, v162
	v_pk_add_f32 v[176:177], v[176:177], 1.0 op_sel_hi:[1,0]
	v_rcp_f32_e32 v163, v163
	v_rcp_f32_e32 v170, v170
	v_rcp_f32_e32 v164, v164
	v_rcp_f32_e32 v171, v171
	v_rcp_f32_e32 v165, v165
	v_rcp_f32_e32 v172, v172
	v_rcp_f32_e32 v166, v166
	v_rcp_f32_e32 v173, v173
	v_rcp_f32_e32 v167, v167
	v_rcp_f32_e32 v174, v174
	v_rcp_f32_e32 v168, v168
	v_rcp_f32_e32 v175, v175
	v_rcp_f32_e32 v169, v169
	v_rcp_f32_e32 v176, v176
	v_pk_mul_f32 v[162:163], v[124:125], v[162:163]
	v_rcp_f32_e32 v177, v177
	v_pk_mul_f32 v[164:165], v[126:127], v[164:165]
	v_pk_mul_f32 v[170:171], v[108:109], v[170:171]
	v_pk_mul_f32 v[166:167], v[116:117], v[166:167]
	v_pk_mul_f32 v[172:173], v[110:111], v[172:173]
	v_pk_mul_f32 v[168:169], v[118:119], v[168:169]
	v_pk_mul_f32 v[174:175], v[100:101], v[174:175]
	v_pk_mul_f32 v[162:163], v[162:163], v[120:121]
	v_pk_mul_f32 v[176:177], v[102:103], v[176:177]
	v_pk_mul_f32 v[164:165], v[164:165], v[122:123]
	v_pk_mul_f32 v[170:171], v[170:171], v[104:105]
	v_pk_mul_f32 v[166:167], v[166:167], v[112:113]
	v_pk_mul_f32 v[172:173], v[172:173], v[106:107]
	v_pk_mul_f32 v[168:169], v[168:169], v[114:115]
	v_pk_mul_f32 v[174:175], v[174:175], v[96:97]
	v_cvt_pk_bf16_f32 v178, v162, v163
	v_pk_mul_f32 v[176:177], v[176:177], v[98:99]
	v_cvt_pk_bf16_f32 v179, v164, v165
	v_cvt_pk_bf16_f32 v182, v170, v171
	v_cvt_pk_bf16_f32 v180, v166, v167
	v_cvt_pk_bf16_f32 v183, v172, v173
	v_cvt_pk_bf16_f32 v181, v168, v169
	v_cvt_pk_bf16_f32 v184, v174, v175
	global_store_dwordx4 v[144:145], v[178:181], off
	v_cvt_pk_bf16_f32 v185, v176, v177
	global_store_dwordx4 v[186:187], v[182:185], off
	v_or_b32_e32 v144, 32, v142
	v_or_b32_e32 v186, 48, v142
	v_mad_i64_i32 v[144:145], s[2:3], v144, s33, v[134:135]
	v_mad_i64_i32 v[186:187], s[2:3], v186, s33, v[134:135]
	v_mul_f32_e32 v162, 0xbfb8aa3b, v92
	v_mul_f32_e32 v170, 0xbfb8aa3b, v76
	v_mul_f32_e32 v163, 0xbfb8aa3b, v93
	v_mul_f32_e32 v171, 0xbfb8aa3b, v77
	v_mul_f32_e32 v164, 0xbfb8aa3b, v94
	v_mul_f32_e32 v172, 0xbfb8aa3b, v78
	v_mul_f32_e32 v165, 0xbfb8aa3b, v95
	v_mul_f32_e32 v173, 0xbfb8aa3b, v79
	v_mul_f32_e32 v166, 0xbfb8aa3b, v84
	v_mul_f32_e32 v174, 0xbfb8aa3b, v68
	v_mul_f32_e32 v167, 0xbfb8aa3b, v85
	v_mul_f32_e32 v175, 0xbfb8aa3b, v69
	v_mul_f32_e32 v168, 0xbfb8aa3b, v86
	v_mul_f32_e32 v176, 0xbfb8aa3b, v70
	v_mul_f32_e32 v169, 0xbfb8aa3b, v87
	v_mul_f32_e32 v177, 0xbfb8aa3b, v71
	v_lshl_add_u64 v[144:145], v[144:145], 0, v[136:137]
	v_lshl_add_u64 v[186:187], v[186:187], 0, v[136:137]
	v_exp_f32_e32 v162, v162
	v_exp_f32_e32 v170, v170
	v_exp_f32_e32 v163, v163
	v_exp_f32_e32 v171, v171
	v_exp_f32_e32 v164, v164
	v_exp_f32_e32 v172, v172
	v_exp_f32_e32 v165, v165
	v_exp_f32_e32 v173, v173
	v_exp_f32_e32 v166, v166
	v_exp_f32_e32 v174, v174
	v_exp_f32_e32 v167, v167
	v_exp_f32_e32 v175, v175
	v_exp_f32_e32 v168, v168
	v_exp_f32_e32 v176, v176
	v_exp_f32_e32 v169, v169
	v_exp_f32_e32 v177, v177
	v_pk_add_f32 v[162:163], v[162:163], 1.0 op_sel_hi:[1,0]
	v_pk_add_f32 v[170:171], v[170:171], 1.0 op_sel_hi:[1,0]
	v_pk_add_f32 v[164:165], v[164:165], 1.0 op_sel_hi:[1,0]
	v_pk_add_f32 v[172:173], v[172:173], 1.0 op_sel_hi:[1,0]
	v_pk_add_f32 v[166:167], v[166:167], 1.0 op_sel_hi:[1,0]
	v_pk_add_f32 v[174:175], v[174:175], 1.0 op_sel_hi:[1,0]
	v_pk_add_f32 v[168:169], v[168:169], 1.0 op_sel_hi:[1,0]
	v_pk_add_f32 v[176:177], v[176:177], 1.0 op_sel_hi:[1,0]
	v_rcp_f32_e32 v162, v162
	v_rcp_f32_e32 v170, v170
	v_rcp_f32_e32 v163, v163
	v_rcp_f32_e32 v171, v171
	v_rcp_f32_e32 v164, v164
	v_rcp_f32_e32 v172, v172
	v_rcp_f32_e32 v165, v165
	v_rcp_f32_e32 v173, v173
	v_rcp_f32_e32 v166, v166
	v_rcp_f32_e32 v174, v174
	v_rcp_f32_e32 v167, v167
	v_rcp_f32_e32 v175, v175
	v_rcp_f32_e32 v168, v168
	v_rcp_f32_e32 v176, v176
	v_rcp_f32_e32 v169, v169
	v_rcp_f32_e32 v177, v177
	v_pk_mul_f32 v[162:163], v[92:93], v[162:163]
	v_pk_mul_f32 v[170:171], v[76:77], v[170:171]
	v_pk_mul_f32 v[164:165], v[94:95], v[164:165]
	v_pk_mul_f32 v[172:173], v[78:79], v[172:173]
	v_pk_mul_f32 v[166:167], v[84:85], v[166:167]
	v_pk_mul_f32 v[174:175], v[68:69], v[174:175]
	v_pk_mul_f32 v[168:169], v[86:87], v[168:169]
	v_pk_mul_f32 v[176:177], v[70:71], v[176:177]
	v_pk_mul_f32 v[162:163], v[162:163], v[88:89]
	v_pk_mul_f32 v[170:171], v[170:171], v[72:73]
	v_pk_mul_f32 v[164:165], v[164:165], v[90:91]
	v_pk_mul_f32 v[172:173], v[172:173], v[74:75]
	v_pk_mul_f32 v[166:167], v[166:167], v[80:81]
	v_pk_mul_f32 v[174:175], v[174:175], v[64:65]
	v_pk_mul_f32 v[168:169], v[168:169], v[82:83]
	v_pk_mul_f32 v[176:177], v[176:177], v[66:67]
	v_cvt_pk_bf16_f32 v178, v162, v163
	v_cvt_pk_bf16_f32 v182, v170, v171
	v_cvt_pk_bf16_f32 v179, v164, v165
	v_cvt_pk_bf16_f32 v183, v172, v173
	v_cvt_pk_bf16_f32 v180, v166, v167
	v_cvt_pk_bf16_f32 v184, v174, v175
	v_cvt_pk_bf16_f32 v181, v168, v169
	v_cvt_pk_bf16_f32 v185, v176, v177
	global_store_dwordx4 v[144:145], v[178:181], off
	global_store_dwordx4 v[186:187], v[182:185], off
	v_add_u32_e32 v144, 0x80, v142
	v_add_u32_e32 v186, 0x90, v142
	v_mad_i64_i32 v[144:145], s[2:3], v144, s33, v[134:135]
	v_mad_i64_i32 v[186:187], s[2:3], v186, s33, v[134:135]
	v_mul_f32_e32 v162, 0xbfb8aa3b, v60
	v_mul_f32_e32 v170, 0xbfb8aa3b, v44
	v_mul_f32_e32 v163, 0xbfb8aa3b, v61
	v_mul_f32_e32 v171, 0xbfb8aa3b, v45
	v_mul_f32_e32 v164, 0xbfb8aa3b, v62
	v_mul_f32_e32 v172, 0xbfb8aa3b, v46
	v_mul_f32_e32 v165, 0xbfb8aa3b, v63
	v_mul_f32_e32 v173, 0xbfb8aa3b, v47
	v_mul_f32_e32 v166, 0xbfb8aa3b, v52
	v_mul_f32_e32 v174, 0xbfb8aa3b, v36
	v_mul_f32_e32 v167, 0xbfb8aa3b, v53
	v_mul_f32_e32 v175, 0xbfb8aa3b, v37
	v_mul_f32_e32 v168, 0xbfb8aa3b, v54
	v_mul_f32_e32 v176, 0xbfb8aa3b, v38
	v_mul_f32_e32 v169, 0xbfb8aa3b, v55
	v_mul_f32_e32 v177, 0xbfb8aa3b, v39
	v_lshl_add_u64 v[144:145], v[144:145], 0, v[136:137]
	v_lshl_add_u64 v[186:187], v[186:187], 0, v[136:137]
	v_exp_f32_e32 v162, v162
	v_exp_f32_e32 v170, v170
	v_exp_f32_e32 v163, v163
	v_exp_f32_e32 v171, v171
	v_exp_f32_e32 v164, v164
	v_exp_f32_e32 v172, v172
	v_exp_f32_e32 v165, v165
	v_exp_f32_e32 v173, v173
	v_exp_f32_e32 v166, v166
	v_exp_f32_e32 v174, v174
	v_exp_f32_e32 v167, v167
	v_exp_f32_e32 v175, v175
	v_exp_f32_e32 v168, v168
	v_exp_f32_e32 v176, v176
	v_exp_f32_e32 v169, v169
	v_exp_f32_e32 v177, v177
	v_pk_add_f32 v[162:163], v[162:163], 1.0 op_sel_hi:[1,0]
	v_pk_add_f32 v[170:171], v[170:171], 1.0 op_sel_hi:[1,0]
	v_pk_add_f32 v[164:165], v[164:165], 1.0 op_sel_hi:[1,0]
	v_pk_add_f32 v[172:173], v[172:173], 1.0 op_sel_hi:[1,0]
	v_pk_add_f32 v[166:167], v[166:167], 1.0 op_sel_hi:[1,0]
	v_pk_add_f32 v[174:175], v[174:175], 1.0 op_sel_hi:[1,0]
	v_pk_add_f32 v[168:169], v[168:169], 1.0 op_sel_hi:[1,0]
	v_pk_add_f32 v[176:177], v[176:177], 1.0 op_sel_hi:[1,0]
	v_rcp_f32_e32 v162, v162
	v_rcp_f32_e32 v170, v170
	v_rcp_f32_e32 v163, v163
	v_rcp_f32_e32 v171, v171
	v_rcp_f32_e32 v164, v164
	v_rcp_f32_e32 v172, v172
	v_rcp_f32_e32 v165, v165
	v_rcp_f32_e32 v173, v173
	v_rcp_f32_e32 v166, v166
	v_rcp_f32_e32 v174, v174
	v_rcp_f32_e32 v167, v167
	v_rcp_f32_e32 v175, v175
	v_rcp_f32_e32 v168, v168
	v_rcp_f32_e32 v176, v176
	v_rcp_f32_e32 v169, v169
	v_rcp_f32_e32 v177, v177
	v_pk_mul_f32 v[162:163], v[60:61], v[162:163]
	v_pk_mul_f32 v[170:171], v[44:45], v[170:171]
	v_pk_mul_f32 v[164:165], v[62:63], v[164:165]
	v_pk_mul_f32 v[172:173], v[46:47], v[172:173]
	v_pk_mul_f32 v[166:167], v[52:53], v[166:167]
	v_pk_mul_f32 v[174:175], v[36:37], v[174:175]
	v_pk_mul_f32 v[168:169], v[54:55], v[168:169]
	v_pk_mul_f32 v[176:177], v[38:39], v[176:177]
	v_pk_mul_f32 v[162:163], v[162:163], v[56:57]
	v_pk_mul_f32 v[170:171], v[170:171], v[40:41]
	v_pk_mul_f32 v[164:165], v[164:165], v[58:59]
	v_pk_mul_f32 v[172:173], v[172:173], v[42:43]
	v_pk_mul_f32 v[166:167], v[166:167], v[48:49]
	v_pk_mul_f32 v[174:175], v[174:175], v[32:33]
	v_pk_mul_f32 v[168:169], v[168:169], v[50:51]
	v_pk_mul_f32 v[176:177], v[176:177], v[34:35]
	v_cvt_pk_bf16_f32 v178, v162, v163
	v_cvt_pk_bf16_f32 v182, v170, v171
	v_cvt_pk_bf16_f32 v179, v164, v165
	v_cvt_pk_bf16_f32 v183, v172, v173
	v_cvt_pk_bf16_f32 v180, v166, v167
	v_cvt_pk_bf16_f32 v184, v174, v175
	v_cvt_pk_bf16_f32 v181, v168, v169
	v_cvt_pk_bf16_f32 v185, v176, v177
	global_store_dwordx4 v[144:145], v[178:181], off
	global_store_dwordx4 v[186:187], v[182:185], off
	v_add_u32_e32 v144, 0xa0, v142
	v_add_u32_e32 v186, 0xb0, v142
	v_mad_i64_i32 v[144:145], s[2:3], v144, s33, v[134:135]
	v_mad_i64_i32 v[186:187], s[2:3], v186, s33, v[134:135]
	v_mul_f32_e32 v162, 0xbfb8aa3b, v28
	v_mul_f32_e32 v170, 0xbfb8aa3b, v12
	v_mul_f32_e32 v163, 0xbfb8aa3b, v29
	v_mul_f32_e32 v171, 0xbfb8aa3b, v13
	v_mul_f32_e32 v164, 0xbfb8aa3b, v30
	v_mul_f32_e32 v172, 0xbfb8aa3b, v14
	v_mul_f32_e32 v165, 0xbfb8aa3b, v31
	v_mul_f32_e32 v173, 0xbfb8aa3b, v15
	v_mul_f32_e32 v166, 0xbfb8aa3b, v20
	v_mul_f32_e32 v174, 0xbfb8aa3b, v4
	v_mul_f32_e32 v167, 0xbfb8aa3b, v21
	v_mul_f32_e32 v175, 0xbfb8aa3b, v5
	v_mul_f32_e32 v168, 0xbfb8aa3b, v22
	v_mul_f32_e32 v176, 0xbfb8aa3b, v6
	v_mul_f32_e32 v169, 0xbfb8aa3b, v23
	v_mul_f32_e32 v177, 0xbfb8aa3b, v7
	v_lshl_add_u64 v[144:145], v[144:145], 0, v[136:137]
	v_lshl_add_u64 v[186:187], v[186:187], 0, v[136:137]
	v_exp_f32_e32 v162, v162
	v_exp_f32_e32 v170, v170
	v_exp_f32_e32 v163, v163
	v_exp_f32_e32 v171, v171
	v_exp_f32_e32 v164, v164
	v_exp_f32_e32 v172, v172
	v_exp_f32_e32 v165, v165
	v_exp_f32_e32 v173, v173
	v_exp_f32_e32 v166, v166
	v_exp_f32_e32 v174, v174
	v_exp_f32_e32 v167, v167
	v_exp_f32_e32 v175, v175
	v_exp_f32_e32 v168, v168
	v_exp_f32_e32 v176, v176
	v_exp_f32_e32 v169, v169
	v_exp_f32_e32 v177, v177
	v_pk_add_f32 v[162:163], v[162:163], 1.0 op_sel_hi:[1,0]
	v_pk_add_f32 v[170:171], v[170:171], 1.0 op_sel_hi:[1,0]
	v_pk_add_f32 v[164:165], v[164:165], 1.0 op_sel_hi:[1,0]
	v_pk_add_f32 v[172:173], v[172:173], 1.0 op_sel_hi:[1,0]
	v_pk_add_f32 v[166:167], v[166:167], 1.0 op_sel_hi:[1,0]
	v_pk_add_f32 v[174:175], v[174:175], 1.0 op_sel_hi:[1,0]
	v_pk_add_f32 v[168:169], v[168:169], 1.0 op_sel_hi:[1,0]
	v_pk_add_f32 v[176:177], v[176:177], 1.0 op_sel_hi:[1,0]
	v_rcp_f32_e32 v162, v162
	v_rcp_f32_e32 v170, v170
	v_rcp_f32_e32 v163, v163
	v_rcp_f32_e32 v171, v171
	v_rcp_f32_e32 v164, v164
	v_rcp_f32_e32 v172, v172
	v_rcp_f32_e32 v165, v165
	v_rcp_f32_e32 v173, v173
	v_rcp_f32_e32 v166, v166
	v_rcp_f32_e32 v174, v174
	v_rcp_f32_e32 v167, v167
	v_rcp_f32_e32 v175, v175
	v_rcp_f32_e32 v168, v168
	v_rcp_f32_e32 v176, v176
	v_rcp_f32_e32 v169, v169
	v_rcp_f32_e32 v177, v177
	v_pk_mul_f32 v[162:163], v[28:29], v[162:163]
	v_pk_mul_f32 v[170:171], v[12:13], v[170:171]
	v_pk_mul_f32 v[164:165], v[30:31], v[164:165]
	v_pk_mul_f32 v[172:173], v[14:15], v[172:173]
	v_pk_mul_f32 v[166:167], v[20:21], v[166:167]
	v_pk_mul_f32 v[174:175], v[4:5], v[174:175]
	v_pk_mul_f32 v[168:169], v[22:23], v[168:169]
	v_pk_mul_f32 v[176:177], v[6:7], v[176:177]
	v_pk_mul_f32 v[162:163], v[162:163], v[24:25]
	v_pk_mul_f32 v[170:171], v[170:171], v[8:9]
	v_pk_mul_f32 v[164:165], v[164:165], v[26:27]
	v_pk_mul_f32 v[172:173], v[172:173], v[10:11]
	v_pk_mul_f32 v[166:167], v[166:167], v[16:17]
	v_pk_mul_f32 v[174:175], v[174:175], v[0:1]
	v_pk_mul_f32 v[168:169], v[168:169], v[18:19]
	v_pk_mul_f32 v[176:177], v[176:177], v[2:3]
	v_cvt_pk_bf16_f32 v178, v162, v163
	v_cvt_pk_bf16_f32 v182, v170, v171
	v_cvt_pk_bf16_f32 v179, v164, v165
	v_cvt_pk_bf16_f32 v183, v172, v173
	v_cvt_pk_bf16_f32 v180, v166, v167
	v_cvt_pk_bf16_f32 v184, v174, v175
	v_cvt_pk_bf16_f32 v181, v168, v169
	v_cvt_pk_bf16_f32 v185, v176, v177
	global_store_dwordx4 v[144:145], v[178:181], off
	global_store_dwordx4 v[186:187], v[182:185], off
	s_cbranch_vccz .LBB0_554
	s_waitcnt vmcnt(0)
	s_cmpk_gt_u32 s21, 0xff
	s_cbranch_scc1 .LBB0_559
	s_barrier
